# GLU GEMM epilogue (FGlu) rewritten: glu_b loaded once, Y/z row loads issued 8 steps ahead (ring) instead of one step, same f32 op order
# baseline (speedup 1.0000x reference)
; #define GAS __attribute__((address_space(1)))
; __device__ __forceinline__ float sigmoidf_(float x) { return frcp(1.f + fexp2(-x * LOG2E)); }
; __device__ __forceinline__ u32x4 pack8(f32x4 a, f32x4 b) { u32x4 w; w.x = pk2(a[0], a[1]); w.y = pk2(a[2], a[3]); w.z = pk2(b[0], b[1]); w.w = pk2(b[2], b[3]); return w; }
; __device__ __forceinline__ void unpack8(u32x4 w, f32x4& a, f32x4& b) { a = (f32x4){bf_lo(w.x), bf_hi(w.x), bf_lo(w.y), bf_hi(w.y)}; b = (f32x4){bf_lo(w.z), bf_hi(w.z), bf_lo(w.w), bf_hi(w.w)}; }
;     __device__ __forceinline__ void operator()(const f32x4 (&acc)[2][2][4][2], const Unit& u, int wr, int wc, int fr, int fq) const {
;     ...
;         for (int ai = 0; ai < 2; ++ai)
; #pragma unroll
;             for (int m = 0; m < 4; ++m) {
;                 const int row = u.pm * BM + ai * HALF + wr * 64 + m * 16 + fr;
; #pragma unroll
;                 for (int bj = 0; bj < 2; ++bj) f(u, row, bj * HALF + wc * 32 + 8 * fq, acc[ai][bj][m][0], acc[ai][bj][m][1]);
;     __device__ __forceinline__ void operator()(const Unit& u, int row, int col, f32x4 v0, f32x4 v1) const {
;         const int c = u.pn * 256 + col;
;         const f32x4 b0 = *(const GAS f32x4*)(glu_b + c), b1 = *(const GAS f32x4*)(glu_b + c + 4);
;         f32x4 y0, y1, z0, z1; unpack8(*(const GAS u32x4*)(Y + (size_t)row * 512 + c), y0, y1);
;         GAS bf16_t* zp = P + (size_t)row * PW + PC_ZSSM + c; unpack8(*(const GAS u32x4*)zp, z0, z1);
; #pragma unroll
;         for (int i = 0; i < 4; ++i) { v0[i] = y0[i] * sigmoidf_(v0[i] + b0[i]) * z0[i]; v1[i] = y1[i] * sigmoidf_(v1[i] + b1[i]) * z1[i]; }
;         *(GAS u32x4*)zp = pack8(v0, v1);
;     }
.LBB0_951:
	v_lshl_add_u32 v241, s72, 8, v156
	v_lshl_add_u32 v242, s50, 8, v154
	s_waitcnt lgkmcnt(0)
	v_lshlrev_b32_e32 v243, 2, v241
	global_load_dwordx4 v[176:179], v243, s[8:9]
	global_load_dwordx4 v[180:183], v243, s[8:9] offset:16
	global_load_dwordx4 v[144:147], v243, s[8:9] offset:512
	global_load_dwordx4 v[148:151], v243, s[8:9] offset:528
	v_lshlrev_b32_e32 v241, 1, v241
	v_mul_lo_u32 v152, v242, s71
	v_lshl_add_u32 v153, v242, 10, v241
	v_add_u32_e32 v152, v152, v241
	v_mov_b32_e32 v241, v152
	v_mov_b32_e32 v242, v153
	global_load_dwordx4 v[160:163], v242, s[6:7]
	global_load_dwordx4 v[164:167], v241, s[10:11]
	v_mov_b32_e32 v241, v152
	v_mov_b32_e32 v242, v153
	global_load_dwordx4 v[168:171], v242, s[6:7] offset:256
	global_load_dwordx4 v[172:175], v241, s[10:11] offset:256
	s_mul_i32 s52, s71, 16
	v_add_u32_e32 v241, s52, v152
	v_add_u32_e32 v242, 0x4000, v153
	global_load_dwordx4 v[192:195], v242, s[6:7]
	global_load_dwordx4 v[196:199], v241, s[10:11]
	s_mul_i32 s52, s71, 16
	v_add_u32_e32 v241, s52, v152
	v_add_u32_e32 v242, 0x4000, v153
	global_load_dwordx4 v[200:203], v242, s[6:7] offset:256
	global_load_dwordx4 v[204:207], v241, s[10:11] offset:256
	s_mul_i32 s52, s71, 32
	v_add_u32_e32 v241, s52, v152
	v_add_u32_e32 v242, 0x8000, v153
	global_load_dwordx4 v[208:211], v242, s[6:7]
	global_load_dwordx4 v[212:215], v241, s[10:11]
	s_mul_i32 s52, s71, 32
	v_add_u32_e32 v241, s52, v152
	v_add_u32_e32 v242, 0x8000, v153
	global_load_dwordx4 v[216:219], v242, s[6:7] offset:256
	global_load_dwordx4 v[220:223], v241, s[10:11] offset:256
	s_mul_i32 s52, s71, 48
	v_add_u32_e32 v241, s52, v152
	v_add_u32_e32 v242, 0xc000, v153
	global_load_dwordx4 v[224:227], v242, s[6:7]
	global_load_dwordx4 v[228:231], v241, s[10:11]
	s_mul_i32 s52, s71, 48
	v_add_u32_e32 v241, s52, v152
	v_add_u32_e32 v242, 0xc000, v153
	global_load_dwordx4 v[232:235], v242, s[6:7] offset:256
	global_load_dwordx4 v[236:239], v241, s[10:11] offset:256
	s_waitcnt vmcnt(14)
	v_add_f32_e32 v120, v120, v176
	v_add_f32_e32 v121, v121, v177
	v_add_f32_e32 v122, v122, v178
	v_add_f32_e32 v123, v123, v179
	v_add_f32_e32 v124, v124, v180
	v_add_f32_e32 v125, v125, v181
	v_add_f32_e32 v126, v126, v182
	v_add_f32_e32 v127, v127, v183
	v_mul_f32_e32 v120, 0xbfb8aa3b, v120
	v_mul_f32_e32 v121, 0xbfb8aa3b, v121
	v_mul_f32_e32 v122, 0xbfb8aa3b, v122
	v_mul_f32_e32 v123, 0xbfb8aa3b, v123
	v_mul_f32_e32 v124, 0xbfb8aa3b, v124
	v_mul_f32_e32 v125, 0xbfb8aa3b, v125
	v_mul_f32_e32 v126, 0xbfb8aa3b, v126
	v_mul_f32_e32 v127, 0xbfb8aa3b, v127
	v_exp_f32_e32 v120, v120
	v_exp_f32_e32 v121, v121
	v_exp_f32_e32 v122, v122
	v_exp_f32_e32 v123, v123
	v_exp_f32_e32 v124, v124
	v_exp_f32_e32 v125, v125
	v_exp_f32_e32 v126, v126
	v_exp_f32_e32 v127, v127
	v_lshlrev_b32_e32 v188, 16, v160
	v_and_b32_e32 v189, 0xffff0000, v160
	v_lshlrev_b32_e32 v190, 16, v161
	v_and_b32_e32 v191, 0xffff0000, v161
	v_lshlrev_b32_e32 v244, 16, v162
	v_and_b32_e32 v245, 0xffff0000, v162
	v_lshlrev_b32_e32 v246, 16, v163
	v_and_b32_e32 v247, 0xffff0000, v163
	v_add_f32_e32 v120, 1.0, v120
	v_add_f32_e32 v121, 1.0, v121
	v_add_f32_e32 v122, 1.0, v122
	v_add_f32_e32 v123, 1.0, v123
	v_add_f32_e32 v124, 1.0, v124
	v_add_f32_e32 v125, 1.0, v125
	v_add_f32_e32 v126, 1.0, v126
	v_add_f32_e32 v127, 1.0, v127
	v_rcp_f32_e32 v120, v120
	v_rcp_f32_e32 v121, v121
	v_rcp_f32_e32 v122, v122
	v_rcp_f32_e32 v123, v123
	v_rcp_f32_e32 v124, v124
	v_rcp_f32_e32 v125, v125
	v_rcp_f32_e32 v126, v126
	v_rcp_f32_e32 v127, v127
	s_nop 0
	v_pk_mul_f32 v[120:121], v[120:121], v[188:189]
	v_pk_mul_f32 v[122:123], v[122:123], v[190:191]
	v_pk_mul_f32 v[124:125], v[124:125], v[244:245]
	v_pk_mul_f32 v[126:127], v[126:127], v[246:247]
	v_lshlrev_b32_e32 v188, 16, v164
	v_and_b32_e32 v189, 0xffff0000, v164
	v_lshlrev_b32_e32 v190, 16, v165
	v_and_b32_e32 v191, 0xffff0000, v165
	v_lshlrev_b32_e32 v244, 16, v166
	v_and_b32_e32 v245, 0xffff0000, v166
	v_lshlrev_b32_e32 v246, 16, v167
	v_and_b32_e32 v247, 0xffff0000, v167
	v_pk_mul_f32 v[120:121], v[120:121], v[188:189]
	v_pk_mul_f32 v[122:123], v[122:123], v[190:191]
	v_pk_mul_f32 v[124:125], v[124:125], v[244:245]
	v_pk_mul_f32 v[126:127], v[126:127], v[246:247]
	v_cvt_pk_bf16_f32 v120, v120, v121
	v_cvt_pk_bf16_f32 v121, v122, v123
	v_cvt_pk_bf16_f32 v122, v124, v125
	v_cvt_pk_bf16_f32 v123, v126, v127
	v_mov_b32_e32 v243, v152
	global_store_dwordx4 v243, v[120:123], s[10:11]
	s_mul_i32 s52, s71, 128
	v_add_u32_e32 v241, s52, v152
	v_add_u32_e32 v242, 0x20000, v153
	global_load_dwordx4 v[160:163], v242, s[6:7]
	global_load_dwordx4 v[164:167], v241, s[10:11]
	s_waitcnt vmcnt(15)
; #define GAS __attribute__((address_space(1)))
; __device__ __forceinline__ float sigmoidf_(float x) { return frcp(1.f + fexp2(-x * LOG2E)); }
; __device__ __forceinline__ u32x4 pack8(f32x4 a, f32x4 b) { u32x4 w; w.x = pk2(a[0], a[1]); w.y = pk2(a[2], a[3]); w.z = pk2(b[0], b[1]); w.w = pk2(b[2], b[3]); return w; }
; __device__ __forceinline__ void unpack8(u32x4 w, f32x4& a, f32x4& b) { a = (f32x4){bf_lo(w.x), bf_hi(w.x), bf_lo(w.y), bf_hi(w.y)}; b = (f32x4){bf_lo(w.z), bf_hi(w.z), bf_lo(w.w), bf_hi(w.w)}; }
;     __device__ __forceinline__ void operator()(const f32x4 (&acc)[2][2][4][2], const Unit& u, int wr, int wc, int fr, int fq) const {
;     ...
;         for (int ai = 0; ai < 2; ++ai)
; #pragma unroll
;             for (int m = 0; m < 4; ++m) {
;                 const int row = u.pm * BM + ai * HALF + wr * 64 + m * 16 + fr;
; #pragma unroll
;                 for (int bj = 0; bj < 2; ++bj) f(u, row, bj * HALF + wc * 32 + 8 * fq, acc[ai][bj][m][0], acc[ai][bj][m][1]);
;     __device__ __forceinline__ void operator()(const Unit& u, int row, int col, f32x4 v0, f32x4 v1) const {
;         const int c = u.pn * 256 + col;
;         const f32x4 b0 = *(const GAS f32x4*)(glu_b + c), b1 = *(const GAS f32x4*)(glu_b + c + 4);
;         f32x4 y0, y1, z0, z1; unpack8(*(const GAS u32x4*)(Y + (size_t)row * 512 + c), y0, y1);
;         GAS bf16_t* zp = P + (size_t)row * PW + PC_ZSSM + c; unpack8(*(const GAS u32x4*)zp, z0, z1);
; #pragma unroll
;         for (int i = 0; i < 4; ++i) { v0[i] = y0[i] * sigmoidf_(v0[i] + b0[i]) * z0[i]; v1[i] = y1[i] * sigmoidf_(v1[i] + b1[i]) * z1[i]; }
;         *(GAS u32x4*)zp = pack8(v0, v1);
;     }
	v_add_f32_e32 v116, v116, v144
	v_add_f32_e32 v117, v117, v145
	v_add_f32_e32 v118, v118, v146
	v_add_f32_e32 v119, v119, v147
	v_add_f32_e32 v112, v112, v148
	v_add_f32_e32 v113, v113, v149
	v_add_f32_e32 v114, v114, v150
	v_add_f32_e32 v115, v115, v151
	v_mul_f32_e32 v116, 0xbfb8aa3b, v116
	v_mul_f32_e32 v117, 0xbfb8aa3b, v117
	v_mul_f32_e32 v118, 0xbfb8aa3b, v118
	v_mul_f32_e32 v119, 0xbfb8aa3b, v119
	v_mul_f32_e32 v112, 0xbfb8aa3b, v112
	v_mul_f32_e32 v113, 0xbfb8aa3b, v113
	v_mul_f32_e32 v114, 0xbfb8aa3b, v114
	v_mul_f32_e32 v115, 0xbfb8aa3b, v115
	v_exp_f32_e32 v116, v116
	v_exp_f32_e32 v117, v117
	v_exp_f32_e32 v118, v118
	v_exp_f32_e32 v119, v119
	v_exp_f32_e32 v112, v112
	v_exp_f32_e32 v113, v113
	v_exp_f32_e32 v114, v114
	v_exp_f32_e32 v115, v115
	v_lshlrev_b32_e32 v188, 16, v168
	v_and_b32_e32 v189, 0xffff0000, v168
	v_lshlrev_b32_e32 v190, 16, v169
	v_and_b32_e32 v191, 0xffff0000, v169
	v_lshlrev_b32_e32 v244, 16, v170
	v_and_b32_e32 v245, 0xffff0000, v170
	v_lshlrev_b32_e32 v246, 16, v171
	v_and_b32_e32 v247, 0xffff0000, v171
	v_add_f32_e32 v116, 1.0, v116
	v_add_f32_e32 v117, 1.0, v117
	v_add_f32_e32 v118, 1.0, v118
	v_add_f32_e32 v119, 1.0, v119
	v_add_f32_e32 v112, 1.0, v112
	v_add_f32_e32 v113, 1.0, v113
	v_add_f32_e32 v114, 1.0, v114
	v_add_f32_e32 v115, 1.0, v115
	v_rcp_f32_e32 v116, v116
	v_rcp_f32_e32 v117, v117
	v_rcp_f32_e32 v118, v118
	v_rcp_f32_e32 v119, v119
	v_rcp_f32_e32 v112, v112
	v_rcp_f32_e32 v113, v113
	v_rcp_f32_e32 v114, v114
	v_rcp_f32_e32 v115, v115
	s_nop 0
	v_pk_mul_f32 v[116:117], v[116:117], v[188:189]
	v_pk_mul_f32 v[118:119], v[118:119], v[190:191]
	v_pk_mul_f32 v[112:113], v[112:113], v[244:245]
	v_pk_mul_f32 v[114:115], v[114:115], v[246:247]
	v_lshlrev_b32_e32 v188, 16, v172
	v_and_b32_e32 v189, 0xffff0000, v172
	v_lshlrev_b32_e32 v190, 16, v173
	v_and_b32_e32 v191, 0xffff0000, v173
	v_lshlrev_b32_e32 v244, 16, v174
	v_and_b32_e32 v245, 0xffff0000, v174
	v_lshlrev_b32_e32 v246, 16, v175
	v_and_b32_e32 v247, 0xffff0000, v175
	v_pk_mul_f32 v[116:117], v[116:117], v[188:189]
	v_pk_mul_f32 v[118:119], v[118:119], v[190:191]
	v_pk_mul_f32 v[112:113], v[112:113], v[244:245]
	v_pk_mul_f32 v[114:115], v[114:115], v[246:247]
	v_cvt_pk_bf16_f32 v116, v116, v117
	v_cvt_pk_bf16_f32 v117, v118, v119
	v_cvt_pk_bf16_f32 v118, v112, v113
	v_cvt_pk_bf16_f32 v119, v114, v115
	v_mov_b32_e32 v243, v152
	global_store_dwordx4 v243, v[116:119], s[10:11] offset:256
	s_mul_i32 s52, s71, 128
	v_add_u32_e32 v241, s52, v152
	v_add_u32_e32 v242, 0x20000, v153
	global_load_dwordx4 v[168:171], v242, s[6:7] offset:256
	global_load_dwordx4 v[172:175], v241, s[10:11] offset:256
	s_waitcnt vmcnt(16)
	v_add_f32_e32 v108, v108, v176
	v_add_f32_e32 v109, v109, v177
	v_add_f32_e32 v110, v110, v178
	v_add_f32_e32 v111, v111, v179
	v_add_f32_e32 v104, v104, v180
	v_add_f32_e32 v105, v105, v181
	v_add_f32_e32 v106, v106, v182
	v_add_f32_e32 v107, v107, v183
	v_mul_f32_e32 v108, 0xbfb8aa3b, v108
	v_mul_f32_e32 v109, 0xbfb8aa3b, v109
	v_mul_f32_e32 v110, 0xbfb8aa3b, v110
	v_mul_f32_e32 v111, 0xbfb8aa3b, v111
	v_mul_f32_e32 v104, 0xbfb8aa3b, v104
	v_mul_f32_e32 v105, 0xbfb8aa3b, v105
	v_mul_f32_e32 v106, 0xbfb8aa3b, v106
	v_mul_f32_e32 v107, 0xbfb8aa3b, v107
	v_exp_f32_e32 v108, v108
	v_exp_f32_e32 v109, v109
	v_exp_f32_e32 v110, v110
	v_exp_f32_e32 v111, v111
	v_exp_f32_e32 v104, v104
	v_exp_f32_e32 v105, v105
	v_exp_f32_e32 v106, v106
	v_exp_f32_e32 v107, v107
	v_lshlrev_b32_e32 v188, 16, v192
	v_and_b32_e32 v189, 0xffff0000, v192
	v_lshlrev_b32_e32 v190, 16, v193
	v_and_b32_e32 v191, 0xffff0000, v193
	v_lshlrev_b32_e32 v244, 16, v194
	v_and_b32_e32 v245, 0xffff0000, v194
	v_lshlrev_b32_e32 v246, 16, v195
	v_and_b32_e32 v247, 0xffff0000, v195
	v_add_f32_e32 v108, 1.0, v108
	v_add_f32_e32 v109, 1.0, v109
	v_add_f32_e32 v110, 1.0, v110
	v_add_f32_e32 v111, 1.0, v111
	v_add_f32_e32 v104, 1.0, v104
	v_add_f32_e32 v105, 1.0, v105
	v_add_f32_e32 v106, 1.0, v106
	v_add_f32_e32 v107, 1.0, v107
	v_rcp_f32_e32 v108, v108
	v_rcp_f32_e32 v109, v109
	v_rcp_f32_e32 v110, v110
	v_rcp_f32_e32 v111, v111
	v_rcp_f32_e32 v104, v104
	v_rcp_f32_e32 v105, v105
	v_rcp_f32_e32 v106, v106
	v_rcp_f32_e32 v107, v107
	s_nop 0
	v_pk_mul_f32 v[108:109], v[108:109], v[188:189]
	v_pk_mul_f32 v[110:111], v[110:111], v[190:191]
	v_pk_mul_f32 v[104:105], v[104:105], v[244:245]
	v_pk_mul_f32 v[106:107], v[106:107], v[246:247]
	v_lshlrev_b32_e32 v188, 16, v196
	v_and_b32_e32 v189, 0xffff0000, v196
	v_lshlrev_b32_e32 v190, 16, v197
	v_and_b32_e32 v191, 0xffff0000, v197
	v_lshlrev_b32_e32 v244, 16, v198
	v_and_b32_e32 v245, 0xffff0000, v198
	v_lshlrev_b32_e32 v246, 16, v199
	v_and_b32_e32 v247, 0xffff0000, v199
	v_pk_mul_f32 v[108:109], v[108:109], v[188:189]
	v_pk_mul_f32 v[110:111], v[110:111], v[190:191]
	v_pk_mul_f32 v[104:105], v[104:105], v[244:245]
	v_pk_mul_f32 v[106:107], v[106:107], v[246:247]
	v_cvt_pk_bf16_f32 v108, v108, v109
	v_cvt_pk_bf16_f32 v109, v110, v111
	v_cvt_pk_bf16_f32 v110, v104, v105
	v_cvt_pk_bf16_f32 v111, v106, v107
	s_mul_i32 s52, s71, 16
	v_add_u32_e32 v243, s52, v152
	global_store_dwordx4 v243, v[108:111], s[10:11]
	s_mul_i32 s52, s71, 144
	v_add_u32_e32 v241, s52, v152
	v_add_u32_e32 v242, 0x24000, v153
	global_load_dwordx4 v[192:195], v242, s[6:7]
	global_load_dwordx4 v[196:199], v241, s[10:11]
	s_waitcnt vmcnt(17)
; #define GAS __attribute__((address_space(1)))
; __device__ __forceinline__ float sigmoidf_(float x) { return frcp(1.f + fexp2(-x * LOG2E)); }
; __device__ __forceinline__ u32x4 pack8(f32x4 a, f32x4 b) { u32x4 w; w.x = pk2(a[0], a[1]); w.y = pk2(a[2], a[3]); w.z = pk2(b[0], b[1]); w.w = pk2(b[2], b[3]); return w; }
; __device__ __forceinline__ void unpack8(u32x4 w, f32x4& a, f32x4& b) { a = (f32x4){bf_lo(w.x), bf_hi(w.x), bf_lo(w.y), bf_hi(w.y)}; b = (f32x4){bf_lo(w.z), bf_hi(w.z), bf_lo(w.w), bf_hi(w.w)}; }
;     __device__ __forceinline__ void operator()(const f32x4 (&acc)[2][2][4][2], const Unit& u, int wr, int wc, int fr, int fq) const {
;     ...
;         for (int ai = 0; ai < 2; ++ai)
; #pragma unroll
;             for (int m = 0; m < 4; ++m) {
;                 const int row = u.pm * BM + ai * HALF + wr * 64 + m * 16 + fr;
; #pragma unroll
;                 for (int bj = 0; bj < 2; ++bj) f(u, row, bj * HALF + wc * 32 + 8 * fq, acc[ai][bj][m][0], acc[ai][bj][m][1]);
;     __device__ __forceinline__ void operator()(const Unit& u, int row, int col, f32x4 v0, f32x4 v1) const {
;         const int c = u.pn * 256 + col;
;         const f32x4 b0 = *(const GAS f32x4*)(glu_b + c), b1 = *(const GAS f32x4*)(glu_b + c + 4);
;         f32x4 y0, y1, z0, z1; unpack8(*(const GAS u32x4*)(Y + (size_t)row * 512 + c), y0, y1);
;         GAS bf16_t* zp = P + (size_t)row * PW + PC_ZSSM + c; unpack8(*(const GAS u32x4*)zp, z0, z1);
; #pragma unroll
;         for (int i = 0; i < 4; ++i) { v0[i] = y0[i] * sigmoidf_(v0[i] + b0[i]) * z0[i]; v1[i] = y1[i] * sigmoidf_(v1[i] + b1[i]) * z1[i]; }
;         *(GAS u32x4*)zp = pack8(v0, v1);
;     }
	v_add_f32_e32 v100, v100, v144
	v_add_f32_e32 v101, v101, v145
	v_add_f32_e32 v102, v102, v146
	v_add_f32_e32 v103, v103, v147
	v_add_f32_e32 v96, v96, v148
	v_add_f32_e32 v97, v97, v149
	v_add_f32_e32 v98, v98, v150
	v_add_f32_e32 v99, v99, v151
	v_mul_f32_e32 v100, 0xbfb8aa3b, v100
	v_mul_f32_e32 v101, 0xbfb8aa3b, v101
	v_mul_f32_e32 v102, 0xbfb8aa3b, v102
	v_mul_f32_e32 v103, 0xbfb8aa3b, v103
	v_mul_f32_e32 v96, 0xbfb8aa3b, v96
	v_mul_f32_e32 v97, 0xbfb8aa3b, v97
	v_mul_f32_e32 v98, 0xbfb8aa3b, v98
	v_mul_f32_e32 v99, 0xbfb8aa3b, v99
	v_exp_f32_e32 v100, v100
	v_exp_f32_e32 v101, v101
	v_exp_f32_e32 v102, v102
	v_exp_f32_e32 v103, v103
	v_exp_f32_e32 v96, v96
	v_exp_f32_e32 v97, v97
	v_exp_f32_e32 v98, v98
	v_exp_f32_e32 v99, v99
	v_lshlrev_b32_e32 v188, 16, v200
	v_and_b32_e32 v189, 0xffff0000, v200
	v_lshlrev_b32_e32 v190, 16, v201
	v_and_b32_e32 v191, 0xffff0000, v201
	v_lshlrev_b32_e32 v244, 16, v202
	v_and_b32_e32 v245, 0xffff0000, v202
	v_lshlrev_b32_e32 v246, 16, v203
	v_and_b32_e32 v247, 0xffff0000, v203
	v_add_f32_e32 v100, 1.0, v100
	v_add_f32_e32 v101, 1.0, v101
	v_add_f32_e32 v102, 1.0, v102
	v_add_f32_e32 v103, 1.0, v103
	v_add_f32_e32 v96, 1.0, v96
	v_add_f32_e32 v97, 1.0, v97
	v_add_f32_e32 v98, 1.0, v98
	v_add_f32_e32 v99, 1.0, v99
	v_rcp_f32_e32 v100, v100
	v_rcp_f32_e32 v101, v101
	v_rcp_f32_e32 v102, v102
	v_rcp_f32_e32 v103, v103
	v_rcp_f32_e32 v96, v96
	v_rcp_f32_e32 v97, v97
	v_rcp_f32_e32 v98, v98
	v_rcp_f32_e32 v99, v99
	s_nop 0
	v_pk_mul_f32 v[100:101], v[100:101], v[188:189]
	v_pk_mul_f32 v[102:103], v[102:103], v[190:191]
	v_pk_mul_f32 v[96:97], v[96:97], v[244:245]
	v_pk_mul_f32 v[98:99], v[98:99], v[246:247]
	v_lshlrev_b32_e32 v188, 16, v204
	v_and_b32_e32 v189, 0xffff0000, v204
	v_lshlrev_b32_e32 v190, 16, v205
	v_and_b32_e32 v191, 0xffff0000, v205
	v_lshlrev_b32_e32 v244, 16, v206
	v_and_b32_e32 v245, 0xffff0000, v206
	v_lshlrev_b32_e32 v246, 16, v207
	v_and_b32_e32 v247, 0xffff0000, v207
	v_pk_mul_f32 v[100:101], v[100:101], v[188:189]
	v_pk_mul_f32 v[102:103], v[102:103], v[190:191]
	v_pk_mul_f32 v[96:97], v[96:97], v[244:245]
	v_pk_mul_f32 v[98:99], v[98:99], v[246:247]
	v_cvt_pk_bf16_f32 v100, v100, v101
	v_cvt_pk_bf16_f32 v101, v102, v103
	v_cvt_pk_bf16_f32 v102, v96, v97
	v_cvt_pk_bf16_f32 v103, v98, v99
	s_mul_i32 s52, s71, 16
	v_add_u32_e32 v243, s52, v152
	global_store_dwordx4 v243, v[100:103], s[10:11] offset:256
	s_mul_i32 s52, s71, 144
	v_add_u32_e32 v241, s52, v152
	v_add_u32_e32 v242, 0x24000, v153
	global_load_dwordx4 v[200:203], v242, s[6:7] offset:256
	global_load_dwordx4 v[204:207], v241, s[10:11] offset:256
	s_waitcnt vmcnt(18)
	v_add_f32_e32 v92, v92, v176
	v_add_f32_e32 v93, v93, v177
	v_add_f32_e32 v94, v94, v178
	v_add_f32_e32 v95, v95, v179
	v_add_f32_e32 v88, v88, v180
	v_add_f32_e32 v89, v89, v181
	v_add_f32_e32 v90, v90, v182
	v_add_f32_e32 v91, v91, v183
	v_mul_f32_e32 v92, 0xbfb8aa3b, v92
	v_mul_f32_e32 v93, 0xbfb8aa3b, v93
	v_mul_f32_e32 v94, 0xbfb8aa3b, v94
	v_mul_f32_e32 v95, 0xbfb8aa3b, v95
	v_mul_f32_e32 v88, 0xbfb8aa3b, v88
	v_mul_f32_e32 v89, 0xbfb8aa3b, v89
	v_mul_f32_e32 v90, 0xbfb8aa3b, v90
	v_mul_f32_e32 v91, 0xbfb8aa3b, v91
	v_exp_f32_e32 v92, v92
	v_exp_f32_e32 v93, v93
	v_exp_f32_e32 v94, v94
	v_exp_f32_e32 v95, v95
	v_exp_f32_e32 v88, v88
	v_exp_f32_e32 v89, v89
	v_exp_f32_e32 v90, v90
	v_exp_f32_e32 v91, v91
	v_lshlrev_b32_e32 v188, 16, v208
	v_and_b32_e32 v189, 0xffff0000, v208
	v_lshlrev_b32_e32 v190, 16, v209
	v_and_b32_e32 v191, 0xffff0000, v209
	v_lshlrev_b32_e32 v244, 16, v210
	v_and_b32_e32 v245, 0xffff0000, v210
	v_lshlrev_b32_e32 v246, 16, v211
	v_and_b32_e32 v247, 0xffff0000, v211
	v_add_f32_e32 v92, 1.0, v92
	v_add_f32_e32 v93, 1.0, v93
	v_add_f32_e32 v94, 1.0, v94
	v_add_f32_e32 v95, 1.0, v95
	v_add_f32_e32 v88, 1.0, v88
	v_add_f32_e32 v89, 1.0, v89
	v_add_f32_e32 v90, 1.0, v90
	v_add_f32_e32 v91, 1.0, v91
	v_rcp_f32_e32 v92, v92
	v_rcp_f32_e32 v93, v93
	v_rcp_f32_e32 v94, v94
	v_rcp_f32_e32 v95, v95
	v_rcp_f32_e32 v88, v88
	v_rcp_f32_e32 v89, v89
	v_rcp_f32_e32 v90, v90
	v_rcp_f32_e32 v91, v91
	s_nop 0
	v_pk_mul_f32 v[92:93], v[92:93], v[188:189]
	v_pk_mul_f32 v[94:95], v[94:95], v[190:191]
	v_pk_mul_f32 v[88:89], v[88:89], v[244:245]
	v_pk_mul_f32 v[90:91], v[90:91], v[246:247]
	v_lshlrev_b32_e32 v188, 16, v212
	v_and_b32_e32 v189, 0xffff0000, v212
	v_lshlrev_b32_e32 v190, 16, v213
	v_and_b32_e32 v191, 0xffff0000, v213
	v_lshlrev_b32_e32 v244, 16, v214
	v_and_b32_e32 v245, 0xffff0000, v214
	v_lshlrev_b32_e32 v246, 16, v215
	v_and_b32_e32 v247, 0xffff0000, v215
	v_pk_mul_f32 v[92:93], v[92:93], v[188:189]
	v_pk_mul_f32 v[94:95], v[94:95], v[190:191]
	v_pk_mul_f32 v[88:89], v[88:89], v[244:245]
	v_pk_mul_f32 v[90:91], v[90:91], v[246:247]
	v_cvt_pk_bf16_f32 v92, v92, v93
	v_cvt_pk_bf16_f32 v93, v94, v95
	v_cvt_pk_bf16_f32 v94, v88, v89
	v_cvt_pk_bf16_f32 v95, v90, v91
	s_mul_i32 s52, s71, 32
	v_add_u32_e32 v243, s52, v152
	global_store_dwordx4 v243, v[92:95], s[10:11]
	s_mul_i32 s52, s71, 160
	v_add_u32_e32 v241, s52, v152
	v_add_u32_e32 v242, 0x28000, v153
	global_load_dwordx4 v[208:211], v242, s[6:7]
	global_load_dwordx4 v[212:215], v241, s[10:11]
	s_waitcnt vmcnt(19)
; #define GAS __attribute__((address_space(1)))
; __device__ __forceinline__ float sigmoidf_(float x) { return frcp(1.f + fexp2(-x * LOG2E)); }
; __device__ __forceinline__ u32x4 pack8(f32x4 a, f32x4 b) { u32x4 w; w.x = pk2(a[0], a[1]); w.y = pk2(a[2], a[3]); w.z = pk2(b[0], b[1]); w.w = pk2(b[2], b[3]); return w; }
; __device__ __forceinline__ void unpack8(u32x4 w, f32x4& a, f32x4& b) { a = (f32x4){bf_lo(w.x), bf_hi(w.x), bf_lo(w.y), bf_hi(w.y)}; b = (f32x4){bf_lo(w.z), bf_hi(w.z), bf_lo(w.w), bf_hi(w.w)}; }
;     __device__ __forceinline__ void operator()(const f32x4 (&acc)[2][2][4][2], const Unit& u, int wr, int wc, int fr, int fq) const {
;     ...
;         for (int ai = 0; ai < 2; ++ai)
; #pragma unroll
;             for (int m = 0; m < 4; ++m) {
;                 const int row = u.pm * BM + ai * HALF + wr * 64 + m * 16 + fr;
; #pragma unroll
;                 for (int bj = 0; bj < 2; ++bj) f(u, row, bj * HALF + wc * 32 + 8 * fq, acc[ai][bj][m][0], acc[ai][bj][m][1]);
;     __device__ __forceinline__ void operator()(const Unit& u, int row, int col, f32x4 v0, f32x4 v1) const {
;         const int c = u.pn * 256 + col;
;         const f32x4 b0 = *(const GAS f32x4*)(glu_b + c), b1 = *(const GAS f32x4*)(glu_b + c + 4);
;         f32x4 y0, y1, z0, z1; unpack8(*(const GAS u32x4*)(Y + (size_t)row * 512 + c), y0, y1);
;         GAS bf16_t* zp = P + (size_t)row * PW + PC_ZSSM + c; unpack8(*(const GAS u32x4*)zp, z0, z1);
; #pragma unroll
;         for (int i = 0; i < 4; ++i) { v0[i] = y0[i] * sigmoidf_(v0[i] + b0[i]) * z0[i]; v1[i] = y1[i] * sigmoidf_(v1[i] + b1[i]) * z1[i]; }
;         *(GAS u32x4*)zp = pack8(v0, v1);
;     }
	v_add_f32_e32 v84, v84, v144
	v_add_f32_e32 v85, v85, v145
	v_add_f32_e32 v86, v86, v146
	v_add_f32_e32 v87, v87, v147
	v_add_f32_e32 v80, v80, v148
	v_add_f32_e32 v81, v81, v149
	v_add_f32_e32 v82, v82, v150
	v_add_f32_e32 v83, v83, v151
	v_mul_f32_e32 v84, 0xbfb8aa3b, v84
	v_mul_f32_e32 v85, 0xbfb8aa3b, v85
	v_mul_f32_e32 v86, 0xbfb8aa3b, v86
	v_mul_f32_e32 v87, 0xbfb8aa3b, v87
	v_mul_f32_e32 v80, 0xbfb8aa3b, v80
	v_mul_f32_e32 v81, 0xbfb8aa3b, v81
	v_mul_f32_e32 v82, 0xbfb8aa3b, v82
	v_mul_f32_e32 v83, 0xbfb8aa3b, v83
	v_exp_f32_e32 v84, v84
	v_exp_f32_e32 v85, v85
	v_exp_f32_e32 v86, v86
	v_exp_f32_e32 v87, v87
	v_exp_f32_e32 v80, v80
	v_exp_f32_e32 v81, v81
	v_exp_f32_e32 v82, v82
	v_exp_f32_e32 v83, v83
	v_lshlrev_b32_e32 v188, 16, v216
	v_and_b32_e32 v189, 0xffff0000, v216
	v_lshlrev_b32_e32 v190, 16, v217
	v_and_b32_e32 v191, 0xffff0000, v217
	v_lshlrev_b32_e32 v244, 16, v218
	v_and_b32_e32 v245, 0xffff0000, v218
	v_lshlrev_b32_e32 v246, 16, v219
	v_and_b32_e32 v247, 0xffff0000, v219
	v_add_f32_e32 v84, 1.0, v84
	v_add_f32_e32 v85, 1.0, v85
	v_add_f32_e32 v86, 1.0, v86
	v_add_f32_e32 v87, 1.0, v87
	v_add_f32_e32 v80, 1.0, v80
	v_add_f32_e32 v81, 1.0, v81
	v_add_f32_e32 v82, 1.0, v82
	v_add_f32_e32 v83, 1.0, v83
	v_rcp_f32_e32 v84, v84
	v_rcp_f32_e32 v85, v85
	v_rcp_f32_e32 v86, v86
	v_rcp_f32_e32 v87, v87
	v_rcp_f32_e32 v80, v80
	v_rcp_f32_e32 v81, v81
	v_rcp_f32_e32 v82, v82
	v_rcp_f32_e32 v83, v83
	s_nop 0
	v_pk_mul_f32 v[84:85], v[84:85], v[188:189]
	v_pk_mul_f32 v[86:87], v[86:87], v[190:191]
	v_pk_mul_f32 v[80:81], v[80:81], v[244:245]
	v_pk_mul_f32 v[82:83], v[82:83], v[246:247]
	v_lshlrev_b32_e32 v188, 16, v220
	v_and_b32_e32 v189, 0xffff0000, v220
	v_lshlrev_b32_e32 v190, 16, v221
	v_and_b32_e32 v191, 0xffff0000, v221
	v_lshlrev_b32_e32 v244, 16, v222
	v_and_b32_e32 v245, 0xffff0000, v222
	v_lshlrev_b32_e32 v246, 16, v223
	v_and_b32_e32 v247, 0xffff0000, v223
	v_pk_mul_f32 v[84:85], v[84:85], v[188:189]
	v_pk_mul_f32 v[86:87], v[86:87], v[190:191]
	v_pk_mul_f32 v[80:81], v[80:81], v[244:245]
	v_pk_mul_f32 v[82:83], v[82:83], v[246:247]
	v_cvt_pk_bf16_f32 v84, v84, v85
	v_cvt_pk_bf16_f32 v85, v86, v87
	v_cvt_pk_bf16_f32 v86, v80, v81
	v_cvt_pk_bf16_f32 v87, v82, v83
	s_mul_i32 s52, s71, 32
	v_add_u32_e32 v243, s52, v152
	global_store_dwordx4 v243, v[84:87], s[10:11] offset:256
	s_mul_i32 s52, s71, 160
	v_add_u32_e32 v241, s52, v152
	v_add_u32_e32 v242, 0x28000, v153
	global_load_dwordx4 v[216:219], v242, s[6:7] offset:256
	global_load_dwordx4 v[220:223], v241, s[10:11] offset:256
	s_waitcnt vmcnt(20)
	v_add_f32_e32 v76, v76, v176
	v_add_f32_e32 v77, v77, v177
	v_add_f32_e32 v78, v78, v178
	v_add_f32_e32 v79, v79, v179
	v_add_f32_e32 v72, v72, v180
	v_add_f32_e32 v73, v73, v181
	v_add_f32_e32 v74, v74, v182
	v_add_f32_e32 v75, v75, v183
	v_mul_f32_e32 v76, 0xbfb8aa3b, v76
	v_mul_f32_e32 v77, 0xbfb8aa3b, v77
	v_mul_f32_e32 v78, 0xbfb8aa3b, v78
	v_mul_f32_e32 v79, 0xbfb8aa3b, v79
	v_mul_f32_e32 v72, 0xbfb8aa3b, v72
	v_mul_f32_e32 v73, 0xbfb8aa3b, v73
	v_mul_f32_e32 v74, 0xbfb8aa3b, v74
	v_mul_f32_e32 v75, 0xbfb8aa3b, v75
	v_exp_f32_e32 v76, v76
	v_exp_f32_e32 v77, v77
	v_exp_f32_e32 v78, v78
	v_exp_f32_e32 v79, v79
	v_exp_f32_e32 v72, v72
	v_exp_f32_e32 v73, v73
	v_exp_f32_e32 v74, v74
	v_exp_f32_e32 v75, v75
	v_lshlrev_b32_e32 v188, 16, v224
	v_and_b32_e32 v189, 0xffff0000, v224
	v_lshlrev_b32_e32 v190, 16, v225
	v_and_b32_e32 v191, 0xffff0000, v225
	v_lshlrev_b32_e32 v244, 16, v226
	v_and_b32_e32 v245, 0xffff0000, v226
	v_lshlrev_b32_e32 v246, 16, v227
	v_and_b32_e32 v247, 0xffff0000, v227
	v_add_f32_e32 v76, 1.0, v76
	v_add_f32_e32 v77, 1.0, v77
	v_add_f32_e32 v78, 1.0, v78
	v_add_f32_e32 v79, 1.0, v79
	v_add_f32_e32 v72, 1.0, v72
	v_add_f32_e32 v73, 1.0, v73
	v_add_f32_e32 v74, 1.0, v74
	v_add_f32_e32 v75, 1.0, v75
	v_rcp_f32_e32 v76, v76
	v_rcp_f32_e32 v77, v77
	v_rcp_f32_e32 v78, v78
	v_rcp_f32_e32 v79, v79
	v_rcp_f32_e32 v72, v72
	v_rcp_f32_e32 v73, v73
	v_rcp_f32_e32 v74, v74
	v_rcp_f32_e32 v75, v75
	s_nop 0
	v_pk_mul_f32 v[76:77], v[76:77], v[188:189]
	v_pk_mul_f32 v[78:79], v[78:79], v[190:191]
	v_pk_mul_f32 v[72:73], v[72:73], v[244:245]
	v_pk_mul_f32 v[74:75], v[74:75], v[246:247]
	v_lshlrev_b32_e32 v188, 16, v228
	v_and_b32_e32 v189, 0xffff0000, v228
	v_lshlrev_b32_e32 v190, 16, v229
	v_and_b32_e32 v191, 0xffff0000, v229
	v_lshlrev_b32_e32 v244, 16, v230
	v_and_b32_e32 v245, 0xffff0000, v230
	v_lshlrev_b32_e32 v246, 16, v231
	v_and_b32_e32 v247, 0xffff0000, v231
	v_pk_mul_f32 v[76:77], v[76:77], v[188:189]
	v_pk_mul_f32 v[78:79], v[78:79], v[190:191]
	v_pk_mul_f32 v[72:73], v[72:73], v[244:245]
	v_pk_mul_f32 v[74:75], v[74:75], v[246:247]
	v_cvt_pk_bf16_f32 v76, v76, v77
	v_cvt_pk_bf16_f32 v77, v78, v79
	v_cvt_pk_bf16_f32 v78, v72, v73
	v_cvt_pk_bf16_f32 v79, v74, v75
	s_mul_i32 s52, s71, 48
	v_add_u32_e32 v243, s52, v152
	global_store_dwordx4 v243, v[76:79], s[10:11]
	s_mul_i32 s52, s71, 176
	v_add_u32_e32 v241, s52, v152
	v_add_u32_e32 v242, 0x2c000, v153
	global_load_dwordx4 v[224:227], v242, s[6:7]
	global_load_dwordx4 v[228:231], v241, s[10:11]
	s_waitcnt vmcnt(21)
; #define GAS __attribute__((address_space(1)))
; __device__ __forceinline__ float sigmoidf_(float x) { return frcp(1.f + fexp2(-x * LOG2E)); }
; __device__ __forceinline__ u32x4 pack8(f32x4 a, f32x4 b) { u32x4 w; w.x = pk2(a[0], a[1]); w.y = pk2(a[2], a[3]); w.z = pk2(b[0], b[1]); w.w = pk2(b[2], b[3]); return w; }
; __device__ __forceinline__ void unpack8(u32x4 w, f32x4& a, f32x4& b) { a = (f32x4){bf_lo(w.x), bf_hi(w.x), bf_lo(w.y), bf_hi(w.y)}; b = (f32x4){bf_lo(w.z), bf_hi(w.z), bf_lo(w.w), bf_hi(w.w)}; }
;     __device__ __forceinline__ void operator()(const f32x4 (&acc)[2][2][4][2], const Unit& u, int wr, int wc, int fr, int fq) const {
;     ...
;         for (int ai = 0; ai < 2; ++ai)
; #pragma unroll
;             for (int m = 0; m < 4; ++m) {
;                 const int row = u.pm * BM + ai * HALF + wr * 64 + m * 16 + fr;
; #pragma unroll
;                 for (int bj = 0; bj < 2; ++bj) f(u, row, bj * HALF + wc * 32 + 8 * fq, acc[ai][bj][m][0], acc[ai][bj][m][1]);
;     __device__ __forceinline__ void operator()(const Unit& u, int row, int col, f32x4 v0, f32x4 v1) const {
;         const int c = u.pn * 256 + col;
;         const f32x4 b0 = *(const GAS f32x4*)(glu_b + c), b1 = *(const GAS f32x4*)(glu_b + c + 4);
;         f32x4 y0, y1, z0, z1; unpack8(*(const GAS u32x4*)(Y + (size_t)row * 512 + c), y0, y1);
;         GAS bf16_t* zp = P + (size_t)row * PW + PC_ZSSM + c; unpack8(*(const GAS u32x4*)zp, z0, z1);
; #pragma unroll
;         for (int i = 0; i < 4; ++i) { v0[i] = y0[i] * sigmoidf_(v0[i] + b0[i]) * z0[i]; v1[i] = y1[i] * sigmoidf_(v1[i] + b1[i]) * z1[i]; }
;         *(GAS u32x4*)zp = pack8(v0, v1);
;     }
	v_add_f32_e32 v68, v68, v144
	v_add_f32_e32 v69, v69, v145
	v_add_f32_e32 v70, v70, v146
	v_add_f32_e32 v71, v71, v147
	v_add_f32_e32 v64, v64, v148
	v_add_f32_e32 v65, v65, v149
	v_add_f32_e32 v66, v66, v150
	v_add_f32_e32 v67, v67, v151
	v_mul_f32_e32 v68, 0xbfb8aa3b, v68
	v_mul_f32_e32 v69, 0xbfb8aa3b, v69
	v_mul_f32_e32 v70, 0xbfb8aa3b, v70
	v_mul_f32_e32 v71, 0xbfb8aa3b, v71
	v_mul_f32_e32 v64, 0xbfb8aa3b, v64
	v_mul_f32_e32 v65, 0xbfb8aa3b, v65
	v_mul_f32_e32 v66, 0xbfb8aa3b, v66
	v_mul_f32_e32 v67, 0xbfb8aa3b, v67
	v_exp_f32_e32 v68, v68
	v_exp_f32_e32 v69, v69
	v_exp_f32_e32 v70, v70
	v_exp_f32_e32 v71, v71
	v_exp_f32_e32 v64, v64
	v_exp_f32_e32 v65, v65
	v_exp_f32_e32 v66, v66
	v_exp_f32_e32 v67, v67
	v_lshlrev_b32_e32 v188, 16, v232
	v_and_b32_e32 v189, 0xffff0000, v232
	v_lshlrev_b32_e32 v190, 16, v233
	v_and_b32_e32 v191, 0xffff0000, v233
	v_lshlrev_b32_e32 v244, 16, v234
	v_and_b32_e32 v245, 0xffff0000, v234
	v_lshlrev_b32_e32 v246, 16, v235
	v_and_b32_e32 v247, 0xffff0000, v235
	v_add_f32_e32 v68, 1.0, v68
	v_add_f32_e32 v69, 1.0, v69
	v_add_f32_e32 v70, 1.0, v70
	v_add_f32_e32 v71, 1.0, v71
	v_add_f32_e32 v64, 1.0, v64
	v_add_f32_e32 v65, 1.0, v65
	v_add_f32_e32 v66, 1.0, v66
	v_add_f32_e32 v67, 1.0, v67
	v_rcp_f32_e32 v68, v68
	v_rcp_f32_e32 v69, v69
	v_rcp_f32_e32 v70, v70
	v_rcp_f32_e32 v71, v71
	v_rcp_f32_e32 v64, v64
	v_rcp_f32_e32 v65, v65
	v_rcp_f32_e32 v66, v66
	v_rcp_f32_e32 v67, v67
	s_nop 0
	v_pk_mul_f32 v[68:69], v[68:69], v[188:189]
	v_pk_mul_f32 v[70:71], v[70:71], v[190:191]
	v_pk_mul_f32 v[64:65], v[64:65], v[244:245]
	v_pk_mul_f32 v[66:67], v[66:67], v[246:247]
	v_lshlrev_b32_e32 v188, 16, v236
	v_and_b32_e32 v189, 0xffff0000, v236
	v_lshlrev_b32_e32 v190, 16, v237
	v_and_b32_e32 v191, 0xffff0000, v237
	v_lshlrev_b32_e32 v244, 16, v238
	v_and_b32_e32 v245, 0xffff0000, v238
	v_lshlrev_b32_e32 v246, 16, v239
	v_and_b32_e32 v247, 0xffff0000, v239
	v_pk_mul_f32 v[68:69], v[68:69], v[188:189]
	v_pk_mul_f32 v[70:71], v[70:71], v[190:191]
	v_pk_mul_f32 v[64:65], v[64:65], v[244:245]
	v_pk_mul_f32 v[66:67], v[66:67], v[246:247]
	v_cvt_pk_bf16_f32 v68, v68, v69
	v_cvt_pk_bf16_f32 v69, v70, v71
	v_cvt_pk_bf16_f32 v70, v64, v65
	v_cvt_pk_bf16_f32 v71, v66, v67
	s_mul_i32 s52, s71, 48
	v_add_u32_e32 v243, s52, v152
	global_store_dwordx4 v243, v[68:71], s[10:11] offset:256
	s_mul_i32 s52, s71, 176
	v_add_u32_e32 v241, s52, v152
	v_add_u32_e32 v242, 0x2c000, v153
	global_load_dwordx4 v[232:235], v242, s[6:7] offset:256
	global_load_dwordx4 v[236:239], v241, s[10:11] offset:256
	s_waitcnt vmcnt(21)
	v_add_f32_e32 v60, v60, v176
	v_add_f32_e32 v61, v61, v177
	v_add_f32_e32 v62, v62, v178
	v_add_f32_e32 v63, v63, v179
	v_add_f32_e32 v56, v56, v180
	v_add_f32_e32 v57, v57, v181
	v_add_f32_e32 v58, v58, v182
	v_add_f32_e32 v59, v59, v183
	v_mul_f32_e32 v60, 0xbfb8aa3b, v60
	v_mul_f32_e32 v61, 0xbfb8aa3b, v61
	v_mul_f32_e32 v62, 0xbfb8aa3b, v62
	v_mul_f32_e32 v63, 0xbfb8aa3b, v63
	v_mul_f32_e32 v56, 0xbfb8aa3b, v56
	v_mul_f32_e32 v57, 0xbfb8aa3b, v57
	v_mul_f32_e32 v58, 0xbfb8aa3b, v58
	v_mul_f32_e32 v59, 0xbfb8aa3b, v59
	v_exp_f32_e32 v60, v60
	v_exp_f32_e32 v61, v61
	v_exp_f32_e32 v62, v62
	v_exp_f32_e32 v63, v63
	v_exp_f32_e32 v56, v56
	v_exp_f32_e32 v57, v57
	v_exp_f32_e32 v58, v58
	v_exp_f32_e32 v59, v59
	v_lshlrev_b32_e32 v188, 16, v160
	v_and_b32_e32 v189, 0xffff0000, v160
	v_lshlrev_b32_e32 v190, 16, v161
	v_and_b32_e32 v191, 0xffff0000, v161
	v_lshlrev_b32_e32 v244, 16, v162
	v_and_b32_e32 v245, 0xffff0000, v162
	v_lshlrev_b32_e32 v246, 16, v163
	v_and_b32_e32 v247, 0xffff0000, v163
	v_add_f32_e32 v60, 1.0, v60
	v_add_f32_e32 v61, 1.0, v61
	v_add_f32_e32 v62, 1.0, v62
	v_add_f32_e32 v63, 1.0, v63
	v_add_f32_e32 v56, 1.0, v56
	v_add_f32_e32 v57, 1.0, v57
	v_add_f32_e32 v58, 1.0, v58
	v_add_f32_e32 v59, 1.0, v59
	v_rcp_f32_e32 v60, v60
	v_rcp_f32_e32 v61, v61
	v_rcp_f32_e32 v62, v62
	v_rcp_f32_e32 v63, v63
	v_rcp_f32_e32 v56, v56
	v_rcp_f32_e32 v57, v57
	v_rcp_f32_e32 v58, v58
	v_rcp_f32_e32 v59, v59
	s_nop 0
	v_pk_mul_f32 v[60:61], v[60:61], v[188:189]
	v_pk_mul_f32 v[62:63], v[62:63], v[190:191]
	v_pk_mul_f32 v[56:57], v[56:57], v[244:245]
	v_pk_mul_f32 v[58:59], v[58:59], v[246:247]
	v_lshlrev_b32_e32 v188, 16, v164
	v_and_b32_e32 v189, 0xffff0000, v164
	v_lshlrev_b32_e32 v190, 16, v165
	v_and_b32_e32 v191, 0xffff0000, v165
	v_lshlrev_b32_e32 v244, 16, v166
	v_and_b32_e32 v245, 0xffff0000, v166
	v_lshlrev_b32_e32 v246, 16, v167
	v_and_b32_e32 v247, 0xffff0000, v167
	v_pk_mul_f32 v[60:61], v[60:61], v[188:189]
	v_pk_mul_f32 v[62:63], v[62:63], v[190:191]
	v_pk_mul_f32 v[56:57], v[56:57], v[244:245]
	v_pk_mul_f32 v[58:59], v[58:59], v[246:247]
	v_cvt_pk_bf16_f32 v60, v60, v61
	v_cvt_pk_bf16_f32 v61, v62, v63
	v_cvt_pk_bf16_f32 v62, v56, v57
	v_cvt_pk_bf16_f32 v63, v58, v59
	s_mul_i32 s52, s71, 128
	v_add_u32_e32 v243, s52, v152
	global_store_dwordx4 v243, v[60:63], s[10:11]
	s_waitcnt vmcnt(19)
; #define GAS __attribute__((address_space(1)))
; __device__ __forceinline__ float sigmoidf_(float x) { return frcp(1.f + fexp2(-x * LOG2E)); }
; __device__ __forceinline__ u32x4 pack8(f32x4 a, f32x4 b) { u32x4 w; w.x = pk2(a[0], a[1]); w.y = pk2(a[2], a[3]); w.z = pk2(b[0], b[1]); w.w = pk2(b[2], b[3]); return w; }
; __device__ __forceinline__ void unpack8(u32x4 w, f32x4& a, f32x4& b) { a = (f32x4){bf_lo(w.x), bf_hi(w.x), bf_lo(w.y), bf_hi(w.y)}; b = (f32x4){bf_lo(w.z), bf_hi(w.z), bf_lo(w.w), bf_hi(w.w)}; }
;     __device__ __forceinline__ void operator()(const f32x4 (&acc)[2][2][4][2], const Unit& u, int wr, int wc, int fr, int fq) const {
;     ...
;         for (int ai = 0; ai < 2; ++ai)
; #pragma unroll
;             for (int m = 0; m < 4; ++m) {
;                 const int row = u.pm * BM + ai * HALF + wr * 64 + m * 16 + fr;
; #pragma unroll
;                 for (int bj = 0; bj < 2; ++bj) f(u, row, bj * HALF + wc * 32 + 8 * fq, acc[ai][bj][m][0], acc[ai][bj][m][1]);
;     __device__ __forceinline__ void operator()(const Unit& u, int row, int col, f32x4 v0, f32x4 v1) const {
;         const int c = u.pn * 256 + col;
;         const f32x4 b0 = *(const GAS f32x4*)(glu_b + c), b1 = *(const GAS f32x4*)(glu_b + c + 4);
;         f32x4 y0, y1, z0, z1; unpack8(*(const GAS u32x4*)(Y + (size_t)row * 512 + c), y0, y1);
;         GAS bf16_t* zp = P + (size_t)row * PW + PC_ZSSM + c; unpack8(*(const GAS u32x4*)zp, z0, z1);
; #pragma unroll
;         for (int i = 0; i < 4; ++i) { v0[i] = y0[i] * sigmoidf_(v0[i] + b0[i]) * z0[i]; v1[i] = y1[i] * sigmoidf_(v1[i] + b1[i]) * z1[i]; }
;         *(GAS u32x4*)zp = pack8(v0, v1);
;     }
	v_add_f32_e32 v52, v52, v144
	v_add_f32_e32 v53, v53, v145
	v_add_f32_e32 v54, v54, v146
	v_add_f32_e32 v55, v55, v147
	v_add_f32_e32 v48, v48, v148
	v_add_f32_e32 v49, v49, v149
	v_add_f32_e32 v50, v50, v150
	v_add_f32_e32 v51, v51, v151
	v_mul_f32_e32 v52, 0xbfb8aa3b, v52
	v_mul_f32_e32 v53, 0xbfb8aa3b, v53
	v_mul_f32_e32 v54, 0xbfb8aa3b, v54
	v_mul_f32_e32 v55, 0xbfb8aa3b, v55
	v_mul_f32_e32 v48, 0xbfb8aa3b, v48
	v_mul_f32_e32 v49, 0xbfb8aa3b, v49
	v_mul_f32_e32 v50, 0xbfb8aa3b, v50
	v_mul_f32_e32 v51, 0xbfb8aa3b, v51
	v_exp_f32_e32 v52, v52
	v_exp_f32_e32 v53, v53
	v_exp_f32_e32 v54, v54
	v_exp_f32_e32 v55, v55
	v_exp_f32_e32 v48, v48
	v_exp_f32_e32 v49, v49
	v_exp_f32_e32 v50, v50
	v_exp_f32_e32 v51, v51
	v_lshlrev_b32_e32 v188, 16, v168
	v_and_b32_e32 v189, 0xffff0000, v168
	v_lshlrev_b32_e32 v190, 16, v169
	v_and_b32_e32 v191, 0xffff0000, v169
	v_lshlrev_b32_e32 v244, 16, v170
	v_and_b32_e32 v245, 0xffff0000, v170
	v_lshlrev_b32_e32 v246, 16, v171
	v_and_b32_e32 v247, 0xffff0000, v171
	v_add_f32_e32 v52, 1.0, v52
	v_add_f32_e32 v53, 1.0, v53
	v_add_f32_e32 v54, 1.0, v54
	v_add_f32_e32 v55, 1.0, v55
	v_add_f32_e32 v48, 1.0, v48
	v_add_f32_e32 v49, 1.0, v49
	v_add_f32_e32 v50, 1.0, v50
	v_add_f32_e32 v51, 1.0, v51
	v_rcp_f32_e32 v52, v52
	v_rcp_f32_e32 v53, v53
	v_rcp_f32_e32 v54, v54
	v_rcp_f32_e32 v55, v55
	v_rcp_f32_e32 v48, v48
	v_rcp_f32_e32 v49, v49
	v_rcp_f32_e32 v50, v50
	v_rcp_f32_e32 v51, v51
	s_nop 0
	v_pk_mul_f32 v[52:53], v[52:53], v[188:189]
	v_pk_mul_f32 v[54:55], v[54:55], v[190:191]
	v_pk_mul_f32 v[48:49], v[48:49], v[244:245]
	v_pk_mul_f32 v[50:51], v[50:51], v[246:247]
	v_lshlrev_b32_e32 v188, 16, v172
	v_and_b32_e32 v189, 0xffff0000, v172
	v_lshlrev_b32_e32 v190, 16, v173
	v_and_b32_e32 v191, 0xffff0000, v173
	v_lshlrev_b32_e32 v244, 16, v174
	v_and_b32_e32 v245, 0xffff0000, v174
	v_lshlrev_b32_e32 v246, 16, v175
	v_and_b32_e32 v247, 0xffff0000, v175
	v_pk_mul_f32 v[52:53], v[52:53], v[188:189]
	v_pk_mul_f32 v[54:55], v[54:55], v[190:191]
	v_pk_mul_f32 v[48:49], v[48:49], v[244:245]
	v_pk_mul_f32 v[50:51], v[50:51], v[246:247]
	v_cvt_pk_bf16_f32 v52, v52, v53
	v_cvt_pk_bf16_f32 v53, v54, v55
	v_cvt_pk_bf16_f32 v54, v48, v49
	v_cvt_pk_bf16_f32 v55, v50, v51
	s_mul_i32 s52, s71, 128
	v_add_u32_e32 v243, s52, v152
	global_store_dwordx4 v243, v[52:55], s[10:11] offset:256
	s_waitcnt vmcnt(17)
	v_add_f32_e32 v44, v44, v176
	v_add_f32_e32 v45, v45, v177
	v_add_f32_e32 v46, v46, v178
	v_add_f32_e32 v47, v47, v179
	v_add_f32_e32 v40, v40, v180
	v_add_f32_e32 v41, v41, v181
	v_add_f32_e32 v42, v42, v182
	v_add_f32_e32 v43, v43, v183
	v_mul_f32_e32 v44, 0xbfb8aa3b, v44
	v_mul_f32_e32 v45, 0xbfb8aa3b, v45
	v_mul_f32_e32 v46, 0xbfb8aa3b, v46
	v_mul_f32_e32 v47, 0xbfb8aa3b, v47
	v_mul_f32_e32 v40, 0xbfb8aa3b, v40
	v_mul_f32_e32 v41, 0xbfb8aa3b, v41
	v_mul_f32_e32 v42, 0xbfb8aa3b, v42
	v_mul_f32_e32 v43, 0xbfb8aa3b, v43
	v_exp_f32_e32 v44, v44
	v_exp_f32_e32 v45, v45
	v_exp_f32_e32 v46, v46
	v_exp_f32_e32 v47, v47
	v_exp_f32_e32 v40, v40
	v_exp_f32_e32 v41, v41
	v_exp_f32_e32 v42, v42
	v_exp_f32_e32 v43, v43
	v_lshlrev_b32_e32 v188, 16, v192
	v_and_b32_e32 v189, 0xffff0000, v192
	v_lshlrev_b32_e32 v190, 16, v193
	v_and_b32_e32 v191, 0xffff0000, v193
	v_lshlrev_b32_e32 v244, 16, v194
	v_and_b32_e32 v245, 0xffff0000, v194
	v_lshlrev_b32_e32 v246, 16, v195
	v_and_b32_e32 v247, 0xffff0000, v195
	v_add_f32_e32 v44, 1.0, v44
	v_add_f32_e32 v45, 1.0, v45
	v_add_f32_e32 v46, 1.0, v46
	v_add_f32_e32 v47, 1.0, v47
	v_add_f32_e32 v40, 1.0, v40
	v_add_f32_e32 v41, 1.0, v41
	v_add_f32_e32 v42, 1.0, v42
	v_add_f32_e32 v43, 1.0, v43
	v_rcp_f32_e32 v44, v44
	v_rcp_f32_e32 v45, v45
	v_rcp_f32_e32 v46, v46
	v_rcp_f32_e32 v47, v47
	v_rcp_f32_e32 v40, v40
	v_rcp_f32_e32 v41, v41
	v_rcp_f32_e32 v42, v42
	v_rcp_f32_e32 v43, v43
	s_nop 0
	v_pk_mul_f32 v[44:45], v[44:45], v[188:189]
	v_pk_mul_f32 v[46:47], v[46:47], v[190:191]
	v_pk_mul_f32 v[40:41], v[40:41], v[244:245]
	v_pk_mul_f32 v[42:43], v[42:43], v[246:247]
	v_lshlrev_b32_e32 v188, 16, v196
	v_and_b32_e32 v189, 0xffff0000, v196
	v_lshlrev_b32_e32 v190, 16, v197
	v_and_b32_e32 v191, 0xffff0000, v197
	v_lshlrev_b32_e32 v244, 16, v198
	v_and_b32_e32 v245, 0xffff0000, v198
	v_lshlrev_b32_e32 v246, 16, v199
	v_and_b32_e32 v247, 0xffff0000, v199
	v_pk_mul_f32 v[44:45], v[44:45], v[188:189]
	v_pk_mul_f32 v[46:47], v[46:47], v[190:191]
	v_pk_mul_f32 v[40:41], v[40:41], v[244:245]
	v_pk_mul_f32 v[42:43], v[42:43], v[246:247]
	v_cvt_pk_bf16_f32 v44, v44, v45
	v_cvt_pk_bf16_f32 v45, v46, v47
	v_cvt_pk_bf16_f32 v46, v40, v41
	v_cvt_pk_bf16_f32 v47, v42, v43
	s_mul_i32 s52, s71, 144
	v_add_u32_e32 v243, s52, v152
	global_store_dwordx4 v243, v[44:47], s[10:11]
	s_waitcnt vmcnt(15)
; #define GAS __attribute__((address_space(1)))
; __device__ __forceinline__ float sigmoidf_(float x) { return frcp(1.f + fexp2(-x * LOG2E)); }
; __device__ __forceinline__ u32x4 pack8(f32x4 a, f32x4 b) { u32x4 w; w.x = pk2(a[0], a[1]); w.y = pk2(a[2], a[3]); w.z = pk2(b[0], b[1]); w.w = pk2(b[2], b[3]); return w; }
; __device__ __forceinline__ void unpack8(u32x4 w, f32x4& a, f32x4& b) { a = (f32x4){bf_lo(w.x), bf_hi(w.x), bf_lo(w.y), bf_hi(w.y)}; b = (f32x4){bf_lo(w.z), bf_hi(w.z), bf_lo(w.w), bf_hi(w.w)}; }
;     __device__ __forceinline__ void operator()(const f32x4 (&acc)[2][2][4][2], const Unit& u, int wr, int wc, int fr, int fq) const {
;     ...
;         for (int ai = 0; ai < 2; ++ai)
; #pragma unroll
;             for (int m = 0; m < 4; ++m) {
;                 const int row = u.pm * BM + ai * HALF + wr * 64 + m * 16 + fr;
; #pragma unroll
;                 for (int bj = 0; bj < 2; ++bj) f(u, row, bj * HALF + wc * 32 + 8 * fq, acc[ai][bj][m][0], acc[ai][bj][m][1]);
;     __device__ __forceinline__ void operator()(const Unit& u, int row, int col, f32x4 v0, f32x4 v1) const {
;         const int c = u.pn * 256 + col;
;         const f32x4 b0 = *(const GAS f32x4*)(glu_b + c), b1 = *(const GAS f32x4*)(glu_b + c + 4);
;         f32x4 y0, y1, z0, z1; unpack8(*(const GAS u32x4*)(Y + (size_t)row * 512 + c), y0, y1);
;         GAS bf16_t* zp = P + (size_t)row * PW + PC_ZSSM + c; unpack8(*(const GAS u32x4*)zp, z0, z1);
; #pragma unroll
;         for (int i = 0; i < 4; ++i) { v0[i] = y0[i] * sigmoidf_(v0[i] + b0[i]) * z0[i]; v1[i] = y1[i] * sigmoidf_(v1[i] + b1[i]) * z1[i]; }
;         *(GAS u32x4*)zp = pack8(v0, v1);
;     }
	v_add_f32_e32 v36, v36, v144
	v_add_f32_e32 v37, v37, v145
	v_add_f32_e32 v38, v38, v146
	v_add_f32_e32 v39, v39, v147
	v_add_f32_e32 v32, v32, v148
	v_add_f32_e32 v33, v33, v149
	v_add_f32_e32 v34, v34, v150
	v_add_f32_e32 v35, v35, v151
	v_mul_f32_e32 v36, 0xbfb8aa3b, v36
	v_mul_f32_e32 v37, 0xbfb8aa3b, v37
	v_mul_f32_e32 v38, 0xbfb8aa3b, v38
	v_mul_f32_e32 v39, 0xbfb8aa3b, v39
	v_mul_f32_e32 v32, 0xbfb8aa3b, v32
	v_mul_f32_e32 v33, 0xbfb8aa3b, v33
	v_mul_f32_e32 v34, 0xbfb8aa3b, v34
	v_mul_f32_e32 v35, 0xbfb8aa3b, v35
	v_exp_f32_e32 v36, v36
	v_exp_f32_e32 v37, v37
	v_exp_f32_e32 v38, v38
	v_exp_f32_e32 v39, v39
	v_exp_f32_e32 v32, v32
	v_exp_f32_e32 v33, v33
	v_exp_f32_e32 v34, v34
	v_exp_f32_e32 v35, v35
	v_lshlrev_b32_e32 v188, 16, v200
	v_and_b32_e32 v189, 0xffff0000, v200
	v_lshlrev_b32_e32 v190, 16, v201
	v_and_b32_e32 v191, 0xffff0000, v201
	v_lshlrev_b32_e32 v244, 16, v202
	v_and_b32_e32 v245, 0xffff0000, v202
	v_lshlrev_b32_e32 v246, 16, v203
	v_and_b32_e32 v247, 0xffff0000, v203
	v_add_f32_e32 v36, 1.0, v36
	v_add_f32_e32 v37, 1.0, v37
	v_add_f32_e32 v38, 1.0, v38
	v_add_f32_e32 v39, 1.0, v39
	v_add_f32_e32 v32, 1.0, v32
	v_add_f32_e32 v33, 1.0, v33
	v_add_f32_e32 v34, 1.0, v34
	v_add_f32_e32 v35, 1.0, v35
	v_rcp_f32_e32 v36, v36
	v_rcp_f32_e32 v37, v37
	v_rcp_f32_e32 v38, v38
	v_rcp_f32_e32 v39, v39
	v_rcp_f32_e32 v32, v32
	v_rcp_f32_e32 v33, v33
	v_rcp_f32_e32 v34, v34
	v_rcp_f32_e32 v35, v35
	s_nop 0
	v_pk_mul_f32 v[36:37], v[36:37], v[188:189]
	v_pk_mul_f32 v[38:39], v[38:39], v[190:191]
	v_pk_mul_f32 v[32:33], v[32:33], v[244:245]
	v_pk_mul_f32 v[34:35], v[34:35], v[246:247]
	v_lshlrev_b32_e32 v188, 16, v204
	v_and_b32_e32 v189, 0xffff0000, v204
	v_lshlrev_b32_e32 v190, 16, v205
	v_and_b32_e32 v191, 0xffff0000, v205
	v_lshlrev_b32_e32 v244, 16, v206
	v_and_b32_e32 v245, 0xffff0000, v206
	v_lshlrev_b32_e32 v246, 16, v207
	v_and_b32_e32 v247, 0xffff0000, v207
	v_pk_mul_f32 v[36:37], v[36:37], v[188:189]
	v_pk_mul_f32 v[38:39], v[38:39], v[190:191]
	v_pk_mul_f32 v[32:33], v[32:33], v[244:245]
	v_pk_mul_f32 v[34:35], v[34:35], v[246:247]
	v_cvt_pk_bf16_f32 v36, v36, v37
	v_cvt_pk_bf16_f32 v37, v38, v39
	v_cvt_pk_bf16_f32 v38, v32, v33
	v_cvt_pk_bf16_f32 v39, v34, v35
	s_mul_i32 s52, s71, 144
	v_add_u32_e32 v243, s52, v152
	global_store_dwordx4 v243, v[36:39], s[10:11] offset:256
	s_waitcnt vmcnt(13)
	v_add_f32_e32 v28, v28, v176
	v_add_f32_e32 v29, v29, v177
	v_add_f32_e32 v30, v30, v178
	v_add_f32_e32 v31, v31, v179
	v_add_f32_e32 v24, v24, v180
	v_add_f32_e32 v25, v25, v181
	v_add_f32_e32 v26, v26, v182
	v_add_f32_e32 v27, v27, v183
	v_mul_f32_e32 v28, 0xbfb8aa3b, v28
	v_mul_f32_e32 v29, 0xbfb8aa3b, v29
	v_mul_f32_e32 v30, 0xbfb8aa3b, v30
	v_mul_f32_e32 v31, 0xbfb8aa3b, v31
	v_mul_f32_e32 v24, 0xbfb8aa3b, v24
	v_mul_f32_e32 v25, 0xbfb8aa3b, v25
	v_mul_f32_e32 v26, 0xbfb8aa3b, v26
	v_mul_f32_e32 v27, 0xbfb8aa3b, v27
	v_exp_f32_e32 v28, v28
	v_exp_f32_e32 v29, v29
	v_exp_f32_e32 v30, v30
	v_exp_f32_e32 v31, v31
	v_exp_f32_e32 v24, v24
	v_exp_f32_e32 v25, v25
	v_exp_f32_e32 v26, v26
	v_exp_f32_e32 v27, v27
	v_lshlrev_b32_e32 v188, 16, v208
	v_and_b32_e32 v189, 0xffff0000, v208
	v_lshlrev_b32_e32 v190, 16, v209
	v_and_b32_e32 v191, 0xffff0000, v209
	v_lshlrev_b32_e32 v244, 16, v210
	v_and_b32_e32 v245, 0xffff0000, v210
	v_lshlrev_b32_e32 v246, 16, v211
	v_and_b32_e32 v247, 0xffff0000, v211
	v_add_f32_e32 v28, 1.0, v28
	v_add_f32_e32 v29, 1.0, v29
	v_add_f32_e32 v30, 1.0, v30
	v_add_f32_e32 v31, 1.0, v31
	v_add_f32_e32 v24, 1.0, v24
	v_add_f32_e32 v25, 1.0, v25
	v_add_f32_e32 v26, 1.0, v26
	v_add_f32_e32 v27, 1.0, v27
	v_rcp_f32_e32 v28, v28
	v_rcp_f32_e32 v29, v29
	v_rcp_f32_e32 v30, v30
	v_rcp_f32_e32 v31, v31
	v_rcp_f32_e32 v24, v24
	v_rcp_f32_e32 v25, v25
	v_rcp_f32_e32 v26, v26
	v_rcp_f32_e32 v27, v27
	s_nop 0
	v_pk_mul_f32 v[28:29], v[28:29], v[188:189]
	v_pk_mul_f32 v[30:31], v[30:31], v[190:191]
	v_pk_mul_f32 v[24:25], v[24:25], v[244:245]
	v_pk_mul_f32 v[26:27], v[26:27], v[246:247]
	v_lshlrev_b32_e32 v188, 16, v212
	v_and_b32_e32 v189, 0xffff0000, v212
	v_lshlrev_b32_e32 v190, 16, v213
	v_and_b32_e32 v191, 0xffff0000, v213
	v_lshlrev_b32_e32 v244, 16, v214
	v_and_b32_e32 v245, 0xffff0000, v214
	v_lshlrev_b32_e32 v246, 16, v215
	v_and_b32_e32 v247, 0xffff0000, v215
	v_pk_mul_f32 v[28:29], v[28:29], v[188:189]
	v_pk_mul_f32 v[30:31], v[30:31], v[190:191]
	v_pk_mul_f32 v[24:25], v[24:25], v[244:245]
	v_pk_mul_f32 v[26:27], v[26:27], v[246:247]
	v_cvt_pk_bf16_f32 v28, v28, v29
	v_cvt_pk_bf16_f32 v29, v30, v31
	v_cvt_pk_bf16_f32 v30, v24, v25
	v_cvt_pk_bf16_f32 v31, v26, v27
	s_mul_i32 s52, s71, 160
	v_add_u32_e32 v243, s52, v152
	global_store_dwordx4 v243, v[28:31], s[10:11]
	s_waitcnt vmcnt(11)
; #define GAS __attribute__((address_space(1)))
; __device__ __forceinline__ float sigmoidf_(float x) { return frcp(1.f + fexp2(-x * LOG2E)); }
; __device__ __forceinline__ u32x4 pack8(f32x4 a, f32x4 b) { u32x4 w; w.x = pk2(a[0], a[1]); w.y = pk2(a[2], a[3]); w.z = pk2(b[0], b[1]); w.w = pk2(b[2], b[3]); return w; }
; __device__ __forceinline__ void unpack8(u32x4 w, f32x4& a, f32x4& b) { a = (f32x4){bf_lo(w.x), bf_hi(w.x), bf_lo(w.y), bf_hi(w.y)}; b = (f32x4){bf_lo(w.z), bf_hi(w.z), bf_lo(w.w), bf_hi(w.w)}; }
;     __device__ __forceinline__ void operator()(const f32x4 (&acc)[2][2][4][2], const Unit& u, int wr, int wc, int fr, int fq) const {
;     ...
;         for (int ai = 0; ai < 2; ++ai)
; #pragma unroll
;             for (int m = 0; m < 4; ++m) {
;                 const int row = u.pm * BM + ai * HALF + wr * 64 + m * 16 + fr;
; #pragma unroll
;                 for (int bj = 0; bj < 2; ++bj) f(u, row, bj * HALF + wc * 32 + 8 * fq, acc[ai][bj][m][0], acc[ai][bj][m][1]);
;     __device__ __forceinline__ void operator()(const Unit& u, int row, int col, f32x4 v0, f32x4 v1) const {
;         const int c = u.pn * 256 + col;
;         const f32x4 b0 = *(const GAS f32x4*)(glu_b + c), b1 = *(const GAS f32x4*)(glu_b + c + 4);
;         f32x4 y0, y1, z0, z1; unpack8(*(const GAS u32x4*)(Y + (size_t)row * 512 + c), y0, y1);
;         GAS bf16_t* zp = P + (size_t)row * PW + PC_ZSSM + c; unpack8(*(const GAS u32x4*)zp, z0, z1);
; #pragma unroll
;         for (int i = 0; i < 4; ++i) { v0[i] = y0[i] * sigmoidf_(v0[i] + b0[i]) * z0[i]; v1[i] = y1[i] * sigmoidf_(v1[i] + b1[i]) * z1[i]; }
;         *(GAS u32x4*)zp = pack8(v0, v1);
;     }
	v_add_f32_e32 v20, v20, v144
	v_add_f32_e32 v21, v21, v145
	v_add_f32_e32 v22, v22, v146
	v_add_f32_e32 v23, v23, v147
	v_add_f32_e32 v16, v16, v148
	v_add_f32_e32 v17, v17, v149
	v_add_f32_e32 v18, v18, v150
	v_add_f32_e32 v19, v19, v151
	v_mul_f32_e32 v20, 0xbfb8aa3b, v20
	v_mul_f32_e32 v21, 0xbfb8aa3b, v21
	v_mul_f32_e32 v22, 0xbfb8aa3b, v22
	v_mul_f32_e32 v23, 0xbfb8aa3b, v23
	v_mul_f32_e32 v16, 0xbfb8aa3b, v16
	v_mul_f32_e32 v17, 0xbfb8aa3b, v17
	v_mul_f32_e32 v18, 0xbfb8aa3b, v18
	v_mul_f32_e32 v19, 0xbfb8aa3b, v19
	v_exp_f32_e32 v20, v20
	v_exp_f32_e32 v21, v21
	v_exp_f32_e32 v22, v22
	v_exp_f32_e32 v23, v23
	v_exp_f32_e32 v16, v16
	v_exp_f32_e32 v17, v17
	v_exp_f32_e32 v18, v18
	v_exp_f32_e32 v19, v19
	v_lshlrev_b32_e32 v188, 16, v216
	v_and_b32_e32 v189, 0xffff0000, v216
	v_lshlrev_b32_e32 v190, 16, v217
	v_and_b32_e32 v191, 0xffff0000, v217
	v_lshlrev_b32_e32 v244, 16, v218
	v_and_b32_e32 v245, 0xffff0000, v218
	v_lshlrev_b32_e32 v246, 16, v219
	v_and_b32_e32 v247, 0xffff0000, v219
	v_add_f32_e32 v20, 1.0, v20
	v_add_f32_e32 v21, 1.0, v21
	v_add_f32_e32 v22, 1.0, v22
	v_add_f32_e32 v23, 1.0, v23
	v_add_f32_e32 v16, 1.0, v16
	v_add_f32_e32 v17, 1.0, v17
	v_add_f32_e32 v18, 1.0, v18
	v_add_f32_e32 v19, 1.0, v19
	v_rcp_f32_e32 v20, v20
	v_rcp_f32_e32 v21, v21
	v_rcp_f32_e32 v22, v22
	v_rcp_f32_e32 v23, v23
	v_rcp_f32_e32 v16, v16
	v_rcp_f32_e32 v17, v17
	v_rcp_f32_e32 v18, v18
	v_rcp_f32_e32 v19, v19
	s_nop 0
	v_pk_mul_f32 v[20:21], v[20:21], v[188:189]
	v_pk_mul_f32 v[22:23], v[22:23], v[190:191]
	v_pk_mul_f32 v[16:17], v[16:17], v[244:245]
	v_pk_mul_f32 v[18:19], v[18:19], v[246:247]
	v_lshlrev_b32_e32 v188, 16, v220
	v_and_b32_e32 v189, 0xffff0000, v220
	v_lshlrev_b32_e32 v190, 16, v221
	v_and_b32_e32 v191, 0xffff0000, v221
	v_lshlrev_b32_e32 v244, 16, v222
	v_and_b32_e32 v245, 0xffff0000, v222
	v_lshlrev_b32_e32 v246, 16, v223
	v_and_b32_e32 v247, 0xffff0000, v223
	v_pk_mul_f32 v[20:21], v[20:21], v[188:189]
	v_pk_mul_f32 v[22:23], v[22:23], v[190:191]
	v_pk_mul_f32 v[16:17], v[16:17], v[244:245]
	v_pk_mul_f32 v[18:19], v[18:19], v[246:247]
	v_cvt_pk_bf16_f32 v20, v20, v21
	v_cvt_pk_bf16_f32 v21, v22, v23
	v_cvt_pk_bf16_f32 v22, v16, v17
	v_cvt_pk_bf16_f32 v23, v18, v19
	s_mul_i32 s52, s71, 160
	v_add_u32_e32 v243, s52, v152
	global_store_dwordx4 v243, v[20:23], s[10:11] offset:256
	s_waitcnt vmcnt(9)
	v_add_f32_e32 v12, v12, v176
	v_add_f32_e32 v13, v13, v177
	v_add_f32_e32 v14, v14, v178
	v_add_f32_e32 v15, v15, v179
	v_add_f32_e32 v8, v8, v180
	v_add_f32_e32 v9, v9, v181
	v_add_f32_e32 v10, v10, v182
	v_add_f32_e32 v11, v11, v183
	v_mul_f32_e32 v12, 0xbfb8aa3b, v12
	v_mul_f32_e32 v13, 0xbfb8aa3b, v13
	v_mul_f32_e32 v14, 0xbfb8aa3b, v14
	v_mul_f32_e32 v15, 0xbfb8aa3b, v15
	v_mul_f32_e32 v8, 0xbfb8aa3b, v8
	v_mul_f32_e32 v9, 0xbfb8aa3b, v9
	v_mul_f32_e32 v10, 0xbfb8aa3b, v10
	v_mul_f32_e32 v11, 0xbfb8aa3b, v11
	v_exp_f32_e32 v12, v12
	v_exp_f32_e32 v13, v13
	v_exp_f32_e32 v14, v14
	v_exp_f32_e32 v15, v15
	v_exp_f32_e32 v8, v8
	v_exp_f32_e32 v9, v9
	v_exp_f32_e32 v10, v10
	v_exp_f32_e32 v11, v11
	v_lshlrev_b32_e32 v188, 16, v224
	v_and_b32_e32 v189, 0xffff0000, v224
	v_lshlrev_b32_e32 v190, 16, v225
	v_and_b32_e32 v191, 0xffff0000, v225
	v_lshlrev_b32_e32 v244, 16, v226
	v_and_b32_e32 v245, 0xffff0000, v226
	v_lshlrev_b32_e32 v246, 16, v227
	v_and_b32_e32 v247, 0xffff0000, v227
	v_add_f32_e32 v12, 1.0, v12
	v_add_f32_e32 v13, 1.0, v13
	v_add_f32_e32 v14, 1.0, v14
	v_add_f32_e32 v15, 1.0, v15
	v_add_f32_e32 v8, 1.0, v8
	v_add_f32_e32 v9, 1.0, v9
	v_add_f32_e32 v10, 1.0, v10
	v_add_f32_e32 v11, 1.0, v11
	v_rcp_f32_e32 v12, v12
	v_rcp_f32_e32 v13, v13
	v_rcp_f32_e32 v14, v14
	v_rcp_f32_e32 v15, v15
	v_rcp_f32_e32 v8, v8
	v_rcp_f32_e32 v9, v9
	v_rcp_f32_e32 v10, v10
	v_rcp_f32_e32 v11, v11
	s_nop 0
	v_pk_mul_f32 v[12:13], v[12:13], v[188:189]
	v_pk_mul_f32 v[14:15], v[14:15], v[190:191]
	v_pk_mul_f32 v[8:9], v[8:9], v[244:245]
	v_pk_mul_f32 v[10:11], v[10:11], v[246:247]
	v_lshlrev_b32_e32 v188, 16, v228
	v_and_b32_e32 v189, 0xffff0000, v228
	v_lshlrev_b32_e32 v190, 16, v229
	v_and_b32_e32 v191, 0xffff0000, v229
	v_lshlrev_b32_e32 v244, 16, v230
	v_and_b32_e32 v245, 0xffff0000, v230
	v_lshlrev_b32_e32 v246, 16, v231
	v_and_b32_e32 v247, 0xffff0000, v231
	v_pk_mul_f32 v[12:13], v[12:13], v[188:189]
	v_pk_mul_f32 v[14:15], v[14:15], v[190:191]
	v_pk_mul_f32 v[8:9], v[8:9], v[244:245]
	v_pk_mul_f32 v[10:11], v[10:11], v[246:247]
	v_cvt_pk_bf16_f32 v12, v12, v13
	v_cvt_pk_bf16_f32 v13, v14, v15
	v_cvt_pk_bf16_f32 v14, v8, v9
	v_cvt_pk_bf16_f32 v15, v10, v11
	s_mul_i32 s52, s71, 176
	v_add_u32_e32 v243, s52, v152
	global_store_dwordx4 v243, v[12:15], s[10:11]
	s_waitcnt vmcnt(7)
	v_add_f32_e32 v4, v4, v144
	v_add_f32_e32 v5, v5, v145
	v_add_f32_e32 v6, v6, v146
	v_add_f32_e32 v7, v7, v147
	v_add_f32_e32 v0, v0, v148
	v_add_f32_e32 v1, v1, v149
	v_add_f32_e32 v2, v2, v150
	v_add_f32_e32 v3, v3, v151
	v_mul_f32_e32 v4, 0xbfb8aa3b, v4
	v_mul_f32_e32 v5, 0xbfb8aa3b, v5
	v_mul_f32_e32 v6, 0xbfb8aa3b, v6
	v_mul_f32_e32 v7, 0xbfb8aa3b, v7
	v_mul_f32_e32 v0, 0xbfb8aa3b, v0
	v_mul_f32_e32 v1, 0xbfb8aa3b, v1
	v_mul_f32_e32 v2, 0xbfb8aa3b, v2
	v_mul_f32_e32 v3, 0xbfb8aa3b, v3
	v_exp_f32_e32 v4, v4
	v_exp_f32_e32 v5, v5
	v_exp_f32_e32 v6, v6
	v_exp_f32_e32 v7, v7
	v_exp_f32_e32 v0, v0
	v_exp_f32_e32 v1, v1
	v_exp_f32_e32 v2, v2
	v_exp_f32_e32 v3, v3
	v_lshlrev_b32_e32 v188, 16, v232
	v_and_b32_e32 v189, 0xffff0000, v232
	v_lshlrev_b32_e32 v190, 16, v233
	v_and_b32_e32 v191, 0xffff0000, v233
	v_lshlrev_b32_e32 v244, 16, v234
	v_and_b32_e32 v245, 0xffff0000, v234
	v_lshlrev_b32_e32 v246, 16, v235
	v_and_b32_e32 v247, 0xffff0000, v235
	v_add_f32_e32 v4, 1.0, v4
	v_add_f32_e32 v5, 1.0, v5
	v_add_f32_e32 v6, 1.0, v6
	v_add_f32_e32 v7, 1.0, v7
	v_add_f32_e32 v0, 1.0, v0
	v_add_f32_e32 v1, 1.0, v1
	v_add_f32_e32 v2, 1.0, v2
	v_add_f32_e32 v3, 1.0, v3
	v_rcp_f32_e32 v4, v4
	v_rcp_f32_e32 v5, v5
	v_rcp_f32_e32 v6, v6
	v_rcp_f32_e32 v7, v7
	v_rcp_f32_e32 v0, v0
	v_rcp_f32_e32 v1, v1
	v_rcp_f32_e32 v2, v2
	v_rcp_f32_e32 v3, v3
	s_nop 0
	v_pk_mul_f32 v[4:5], v[4:5], v[188:189]
	v_pk_mul_f32 v[6:7], v[6:7], v[190:191]
	v_pk_mul_f32 v[0:1], v[0:1], v[244:245]
	v_pk_mul_f32 v[2:3], v[2:3], v[246:247]
	v_lshlrev_b32_e32 v188, 16, v236
	v_and_b32_e32 v189, 0xffff0000, v236
	v_lshlrev_b32_e32 v190, 16, v237
	v_and_b32_e32 v191, 0xffff0000, v237
	v_lshlrev_b32_e32 v244, 16, v238
	v_and_b32_e32 v245, 0xffff0000, v238
	v_lshlrev_b32_e32 v246, 16, v239
	v_and_b32_e32 v247, 0xffff0000, v239
	v_pk_mul_f32 v[4:5], v[4:5], v[188:189]
	v_pk_mul_f32 v[6:7], v[6:7], v[190:191]
	v_pk_mul_f32 v[0:1], v[0:1], v[244:245]
	v_pk_mul_f32 v[2:3], v[2:3], v[246:247]
	v_cvt_pk_bf16_f32 v4, v4, v5
	v_cvt_pk_bf16_f32 v5, v6, v7
	v_cvt_pk_bf16_f32 v6, v0, v1
	v_cvt_pk_bf16_f32 v7, v2, v3
	s_mul_i32 s52, s71, 176
	v_add_u32_e32 v243, s52, v152
	global_store_dwordx4 v243, v[4:7], s[10:11] offset:256
	s_andn2_b64 vcc, exec, s[4:5]
	s_mov_b64 s[4:5], -1
	s_cbranch_vccnz .LBB0_939
	s_andn2_b64 vcc, exec, s[28:29]
	s_cbranch_vccnz .LBB0_938
	s_barrier
	s_branch .LBB0_938
